# attention loop: static priority raise for waves 4-7 (second wave on each SIMD) while in the tile loop
# speedup vs baseline: 1.0008x; 1.0008x over previous
; template <bool SAMPLE> __device__ __forceinline__ void attn_unit16(const Ctx& c, LAS unsigned char* lds, int b, int h, int qb, int wave_s) {
;     ...
;     for (int j = 0; j < ntiles; j += 2) {
;         ITER16(j, pfa, pfb, 0, 1);
;         if (j + 1 < ntiles) ITER16(j + 1, pfb, pfa, 1, 0);
;     }
.LBB0_836:
	s_cmp_lt_u32 s33, 0x100
	s_cbranch_scc1 .Lq1_prio_skip
	s_setprio 1

; #define LAS __attribute__((address_space(3)))
; __device__ __forceinline__ int fresh_tid(int wave_s) { unsigned m = ~0u; asm volatile("" : "+s"(m)); int t = wave_s * 64 + (int)__builtin_amdgcn_mbcnt_hi(m, __builtin_amdgcn_mbcnt_lo(m, 0u)); asm volatile("" : "+v"(t)); return t; }
; template <bool SAMPLE> __device__ __forceinline__ void attn_unit16(const Ctx& c, LAS unsigned char* lds, int b, int h, int qb, int wave_s) {
;     ...
;     const int lane2 = fresh_tid(wave_s) & 63, c16b = lane2 & 15, q4b = lane2 >> 4;
;     LAS float* X = (LAS float*)lds;
;     if (active) {
;         float lam;
;         { const float a = c.lq1[lane2] * c.lk1[lane2], bb = c.lq2[lane2] * c.lk2[lane2]; lam = __expf(wave_sum(a)) - __expf(wave_sum(bb)) + 0.2f; }
; #pragma unroll
;         for (int qt = 0; qt < NQT; ++qt) { float l = ls[qt] + __shfl_xor(ls[qt], 16); l += __shfl_xor(l, 32);
;             const float inv = (mp ? lam : 1.f) / l;
; #pragma unroll
;             for (int i = 0; i < 4; ++i) { const float fi = __shfl(inv, 4 * q4b + i);
; #pragma unroll
;                 for (int et = 0; et < 8; ++et) o[qt][et][i] *= fi; } }
.LBB0_884:
	s_setprio 0
	s_mov_b32 s0, -1
	v_and_b32_e32 v215, 64, v212
	v_mbcnt_lo_u32_b32 v0, s0, 0
	v_mbcnt_hi_u32_b32 v0, s0, v0
	s_waitcnt vmcnt(1)
	v_add_u32_e32 v7, s33, v0
	v_xor_b32_e32 v5, 1, v212
	v_and_b32_e32 v6, 63, v7
	v_lshlrev_b32_e32 v0, 2, v6
	global_load_dword v2, v0, s[18:19]
	global_load_dword v3, v0, s[20:21]
	global_load_dword v4, v0, s[22:23]
	s_nop 0
	global_load_dword v0, v0, s[24:25]
	s_waitcnt vmcnt(4)
	v_add_u32_e32 v13, 64, v215
	v_cmp_lt_i32_e32 vcc, v5, v13
	v_xor_b32_e32 v8, 2, v212
	v_xor_b32_e32 v9, 4, v212
	v_cndmask_b32_e32 v5, v212, v5, vcc
	v_lshlrev_b32_e32 v210, 2, v5
	v_cmp_lt_i32_e32 vcc, v8, v13
	v_xor_b32_e32 v10, 8, v212
	v_xor_b32_e32 v11, 16, v212
	v_cndmask_b32_e32 v8, v212, v8, vcc
	v_lshlrev_b32_e32 v211, 2, v8
	v_cmp_lt_i32_e32 vcc, v9, v13
	v_xor_b32_e32 v12, 32, v212
	s_cmp_eq_u32 s81, 0
	v_cndmask_b32_e32 v9, v212, v9, vcc
	v_lshlrev_b32_e32 v214, 2, v9
	v_cmp_lt_i32_e32 vcc, v10, v13
	s_cselect_b64 s[2:3], -1, 0
	v_lshrrev_b32_e32 v9, 2, v7
	v_cndmask_b32_e32 v10, v212, v10, vcc
	v_cmp_lt_i32_e32 vcc, v11, v13
	v_lshlrev_b32_e32 v213, 2, v10
	s_cmp_lg_u32 s81, 0
	v_cndmask_b32_e32 v11, v212, v11, vcc
	v_cmp_lt_i32_e32 vcc, v12, v13
	v_lshlrev_b32_e32 v217, 2, v11
	ds_bpermute_b32 v8, v217, v199
	s_waitcnt lgkmcnt(0)
	v_add_f32_e32 v8, v199, v8
	s_waitcnt vmcnt(2)
	v_mul_f32_e32 v5, v2, v3
	ds_bpermute_b32 v5, v210, v5
	s_waitcnt vmcnt(0)
	v_mul_f32_e32 v14, v4, v0
	ds_bpermute_b32 v14, v210, v14
	s_waitcnt lgkmcnt(1)
	v_fmac_f32_e32 v5, v2, v3
	v_cndmask_b32_e32 v3, v212, v12, vcc
	s_waitcnt lgkmcnt(0)
	v_fmac_f32_e32 v14, v4, v0
	ds_bpermute_b32 v0, v211, v5
	ds_bpermute_b32 v2, v211, v14
	v_lshlrev_b32_e32 v216, 2, v3
	ds_bpermute_b32 v12, v216, v8
	s_waitcnt lgkmcnt(2)
	v_add_f32_e32 v0, v5, v0
	s_waitcnt lgkmcnt(1)
	v_add_f32_e32 v2, v14, v2
	ds_bpermute_b32 v4, v214, v0
	ds_bpermute_b32 v5, v214, v2
	s_waitcnt lgkmcnt(1)
	v_add_f32_e32 v0, v0, v4
	s_waitcnt lgkmcnt(0)
	v_add_f32_e32 v2, v2, v5
	ds_bpermute_b32 v3, v213, v0
	ds_bpermute_b32 v4, v213, v2
	ds_bpermute_b32 v5, v217, v198
	s_waitcnt lgkmcnt(2)
	v_add_f32_e32 v0, v0, v3
	s_waitcnt lgkmcnt(1)
	v_add_f32_e32 v2, v2, v4
	ds_bpermute_b32 v3, v217, v0
	ds_bpermute_b32 v10, v217, v2
	s_waitcnt lgkmcnt(2)
	v_add_f32_e32 v5, v198, v5
	ds_bpermute_b32 v11, v216, v5
	v_and_b32_e32 v4, 12, v9
	s_waitcnt lgkmcnt(2)
	v_add_f32_e32 v0, v0, v3
	s_waitcnt lgkmcnt(1)
	v_add_f32_e32 v2, v2, v10
	ds_bpermute_b32 v3, v216, v0
	ds_bpermute_b32 v10, v216, v2
	v_or_b32_e32 v9, v215, v4
	v_lshlrev_b32_e32 v9, 2, v9
	s_waitcnt lgkmcnt(1)
	v_add_f32_e32 v0, v0, v3
	s_waitcnt lgkmcnt(0)
	v_add_f32_e32 v2, v2, v10
	v_mul_f32_e32 v0, 0x3fb8aa3b, v0
	v_mul_f32_e32 v2, 0x3fb8aa3b, v2
	v_exp_f32_e32 v0, v0
	v_exp_f32_e32 v2, v2
	v_add_f32_e32 v3, v5, v11
	v_add_f32_e32 v5, v8, v12
	v_sub_f32_e32 v0, v0, v2
	v_add_f32_e32 v0, 0x3e4ccccd, v0
	v_cndmask_b32_e64 v0, v0, 1.0, s[2:3]
	v_div_scale_f32 v2, s[0:1], v3, v3, v0
	v_rcp_f32_e32 v11, v2
	v_div_scale_f32 v10, s[0:1], v5, v5, v0
	v_rcp_f32_e32 v12, v10
	v_fma_f32 v14, -v2, v11, 1.0
	v_div_scale_f32 v8, vcc, v0, v3, v0
	v_fmac_f32_e32 v11, v14, v11
	v_fma_f32 v15, -v10, v12, 1.0
	v_mul_f32_e32 v14, v8, v11
	v_div_scale_f32 v13, s[0:1], v0, v5, v0
	v_fmac_f32_e32 v12, v15, v12
	v_fma_f32 v16, -v2, v14, v8
	v_mul_f32_e32 v15, v13, v12
	v_fmac_f32_e32 v14, v16, v11
	v_fma_f32 v17, -v10, v15, v13
	v_fma_f32 v2, -v2, v14, v8
	v_fmac_f32_e32 v15, v17, v12
	v_div_fmas_f32 v2, v2, v11, v14
	v_fma_f32 v8, -v10, v15, v13
	v_div_fixup_f32 v2, v2, v3, v0
	s_mov_b64 vcc, s[0:1]
	v_div_fmas_f32 v3, v8, v12, v15
	ds_bpermute_b32 v8, v9, v2
	v_div_fixup_f32 v13, v3, v5, v0
	ds_bpermute_b32 v10, v9, v2 offset:4
	ds_bpermute_b32 v11, v9, v2 offset:8
	ds_bpermute_b32 v12, v9, v2 offset:12
	ds_bpermute_b32 v16, v9, v13
	s_waitcnt lgkmcnt(4)
	v_mul_f32_e32 v14, v128, v8
	v_mul_f32_e32 v15, v124, v8
	v_mul_f32_e32 v19, v116, v8
	v_mul_f32_e32 v18, v104, v8
	v_mul_f32_e32 v5, v88, v8
	v_mul_f32_e32 v3, v80, v8
	v_mul_f32_e32 v2, v68, v8
	v_mul_f32_e32 v0, v56, v8
	ds_bpermute_b32 v8, v9, v13 offset:4
	s_waitcnt lgkmcnt(4)
	v_mul_f32_e32 v113, v129, v10
	v_mul_f32_e32 v114, v125, v10
	v_mul_f32_e32 v112, v117, v10
	v_mul_f32_e32 v105, v105, v10
	v_mul_f32_e32 v104, v89, v10
	v_mul_f32_e32 v95, v81, v10
	v_mul_f32_e32 v94, v69, v10
	v_mul_f32_e32 v93, v57, v10
	s_waitcnt lgkmcnt(3)
	v_mul_f32_e32 v85, v82, v11
	v_mul_f32_e32 v82, v58, v11
	s_waitcnt lgkmcnt(2)
	v_mul_f32_e32 v69, v59, v12
	s_waitcnt lgkmcnt(1)
	v_mul_f32_e32 v59, v52, v16
	v_mul_f32_e32 v58, v48, v16
	s_waitcnt lgkmcnt(0)
	v_mul_f32_e32 v48, v121, v8
	v_mul_f32_e32 v52, v109, v8
	v_mul_f32_e32 v45, v101, v8
	v_mul_f32_e32 v44, v97, v8
	ds_bpermute_b32 v10, v9, v13 offset:8
	v_mul_f32_e32 v57, v77, v8
	v_mul_f32_e32 v56, v65, v8
	v_mul_f32_e32 v47, v53, v8
	v_mul_f32_e32 v46, v49, v8
	ds_bpermute_b32 v8, v9, v13 offset:12
	v_mul_f32_e32 v89, v130, v11
	v_mul_f32_e32 v92, v126, v11
	v_mul_f32_e32 v88, v118, v11
	v_mul_f32_e32 v87, v106, v11
	v_mul_f32_e32 v86, v90, v11
	v_mul_f32_e32 v84, v70, v11
	v_mul_f32_e32 v80, v131, v12
	v_mul_f32_e32 v81, v127, v12
	v_mul_f32_e32 v75, v119, v12
	v_mul_f32_e32 v74, v107, v12
	v_mul_f32_e32 v73, v91, v12
	v_mul_f32_e32 v72, v83, v12
	v_mul_f32_e32 v70, v71, v12
	v_mul_f32_e32 v63, v120, v16
	v_mul_f32_e32 v68, v108, v16
	v_mul_f32_e32 v61, v100, v16
	v_mul_f32_e32 v60, v96, v16
	v_mul_f32_e32 v27, v76, v16
	v_mul_f32_e32 v26, v64, v16
	s_waitcnt lgkmcnt(1)
	v_mul_f32_e32 v40, v122, v10
	v_mul_f32_e32 v41, v110, v10
	v_mul_f32_e32 v37, v102, v10
	v_mul_f32_e32 v36, v98, v10
	v_mul_f32_e32 v43, v78, v10
	v_mul_f32_e32 v42, v66, v10
	v_mul_f32_e32 v39, v54, v10
	v_mul_f32_e32 v38, v50, v10
	s_waitcnt lgkmcnt(0)
	v_mul_f32_e32 v34, v123, v8
	v_mul_f32_e32 v35, v111, v8
	v_mul_f32_e32 v33, v103, v8
	v_mul_f32_e32 v32, v99, v8
	v_mul_f32_e32 v31, v79, v8
	v_mul_f32_e32 v30, v67, v8
	v_mul_f32_e32 v29, v55, v8
	v_mul_f32_e32 v28, v51, v8
	s_cbranch_scc0 .LBB0_886
; template <bool SAMPLE> __device__ __forceinline__ void attn_unit16(const Ctx& c, LAS unsigned char* lds, int b, int h, int qb, int wave_s) {
;     ...
;         if (mp) {
; #pragma unroll
;             for (int qt = 0; qt < NQT; ++qt)
; #pragma unroll
;                 for (int et = 0; et < 8; ++et)
; #pragma unroll
;                     for (int i = 0; i < 4; ++i) X[(g * 64 + qt * 32 + et * 4 + i) * 64 + lane2] = o[qt][et][i];
;         }
	s_lshl_b32 s0, s63, 14
	s_add_i32 s0, s0, 0
	v_lshl_add_u32 v8, v6, 2, s0
	ds_write2st64_b32 v8, v14, v113 offset1:1
	ds_write2st64_b32 v8, v89, v80 offset0:2 offset1:3
	ds_write2st64_b32 v8, v15, v114 offset0:4 offset1:5
	ds_write2st64_b32 v8, v92, v81 offset0:6 offset1:7
	ds_write2st64_b32 v8, v19, v112 offset0:8 offset1:9
	ds_write2st64_b32 v8, v88, v75 offset0:10 offset1:11
	ds_write2st64_b32 v8, v18, v105 offset0:12 offset1:13
	ds_write2st64_b32 v8, v87, v74 offset0:14 offset1:15
	ds_write2st64_b32 v8, v5, v104 offset0:16 offset1:17
	ds_write2st64_b32 v8, v86, v73 offset0:18 offset1:19
	ds_write2st64_b32 v8, v3, v95 offset0:20 offset1:21
	ds_write2st64_b32 v8, v85, v72 offset0:22 offset1:23
	ds_write2st64_b32 v8, v2, v94 offset0:24 offset1:25
	ds_write2st64_b32 v8, v84, v70 offset0:26 offset1:27
	ds_write2st64_b32 v8, v0, v93 offset0:28 offset1:29
	ds_write2st64_b32 v8, v82, v69 offset0:30 offset1:31
	ds_write2st64_b32 v8, v63, v48 offset0:32 offset1:33
	ds_write2st64_b32 v8, v40, v34 offset0:34 offset1:35
	ds_write2st64_b32 v8, v68, v52 offset0:36 offset1:37
	ds_write2st64_b32 v8, v41, v35 offset0:38 offset1:39
	ds_write2st64_b32 v8, v61, v45 offset0:40 offset1:41
	ds_write2st64_b32 v8, v37, v33 offset0:42 offset1:43
	ds_write2st64_b32 v8, v60, v44 offset0:44 offset1:45
	ds_write2st64_b32 v8, v36, v32 offset0:46 offset1:47
	ds_write2st64_b32 v8, v27, v57 offset0:48 offset1:49
	ds_write2st64_b32 v8, v43, v31 offset0:50 offset1:51
	ds_write2st64_b32 v8, v26, v56 offset0:52 offset1:53
	ds_write2st64_b32 v8, v42, v30 offset0:54 offset1:55
	ds_write2st64_b32 v8, v59, v47 offset0:56 offset1:57
	ds_write2st64_b32 v8, v39, v29 offset0:58 offset1:59
	ds_write2st64_b32 v8, v58, v46 offset0:60 offset1:61
	ds_write2st64_b32 v8, v38, v28 offset0:62 offset1:63
